# final-norm pipelined + in-proj K-loop: 2 of the 6 LDS-DMA loads of each 6-DMA load segment moved into the following MFMA segment (vmcnt 8->6 at those waits)
# speedup vs baseline: 1.0051x; 1.0051x over previous
.LBB0_293:
	s_cmp_eq_u32 s57, 28
	s_cselect_b32 s42, s10, s19
	s_cselect_b32 s43, s11, s54
	s_cselect_b32 s40, s26, s55
	s_cselect_b32 s41, s27, s56
	s_add_u32 s38, s42, 0x80
	s_addc_u32 s39, s43, 0
	s_add_i32 s60, 0, 0x10000
	s_add_i32 s61, 0, 0x14000
	v_add_u32_e32 v70, s60, v207
	v_add_u32_e32 v110, s61, v207
	ds_read_b128 v[42:45], v70
	ds_read_b128 v[46:49], v70 offset:1024
	ds_read_b128 v[66:69], v70 offset:2048
	ds_read_b128 v[70:73], v70 offset:3072
	ds_read_b128 v[86:89], v110
	ds_read_b128 v[90:93], v110 offset:1024
	ds_read_b128 v[106:109], v110 offset:2048
	ds_read_b128 v[110:113], v110 offset:3072
	s_add_u32 s58, s19, 0x7ff80
	s_addc_u32 s59, s54, 0
	ds_read_b128 v[130:133], v237
	ds_read_b128 v[134:137], v237 offset:1024
	ds_read_b128 v[154:157], v237 offset:2048
	ds_read_b128 v[158:161], v237 offset:3072
	ds_read_b128 v[178:181], v237 offset:4096
	ds_read_b128 v[182:185], v237 offset:5120
	ds_read_b128 v[186:189], v237 offset:6144
	ds_read_b128 v[190:193], v237 offset:7168
	s_add_i32 m0, s46, 0xc000
	v_lshl_add_u64 v[194:195], s[58:59], 0, v[208:209]
	s_add_u32 s58, s58, 0x40000
	s_addc_u32 s59, s59, 0
	global_load_lds_dwordx4 v[194:195], off
	s_add_i32 m0, s46, 0xe000
	v_lshl_add_u64 v[194:195], s[58:59], 0, v[208:209]
	global_load_lds_dwordx4 v[194:195], off
	s_waitcnt vmcnt(8)
	s_waitcnt lgkmcnt(0)
	s_barrier
	s_setprio 1
	s_waitcnt lgkmcnt(0)
	v_mfma_f32_16x16x32_bf16 v[174:177], v[42:45], v[130:133], v[174:177]
	v_mfma_f32_16x16x32_bf16 v[170:173], v[66:69], v[130:133], v[170:173]
	v_mfma_f32_16x16x32_bf16 v[150:153], v[42:45], v[154:157], v[150:153]
	v_mfma_f32_16x16x32_bf16 v[146:149], v[66:69], v[154:157], v[146:149]
	v_mfma_f32_16x16x32_bf16 v[126:129], v[42:45], v[178:181], v[126:129]
	v_mfma_f32_16x16x32_bf16 v[122:125], v[66:69], v[178:181], v[122:125]
	v_mfma_f32_16x16x32_bf16 v[102:105], v[42:45], v[186:189], v[102:105]
	v_mfma_f32_16x16x32_bf16 v[98:101], v[66:69], v[186:189], v[98:101]
	v_mfma_f32_16x16x32_bf16 v[174:177], v[46:49], v[134:137], v[174:177]
	v_mfma_f32_16x16x32_bf16 v[170:173], v[70:73], v[134:137], v[170:173]
	v_mfma_f32_16x16x32_bf16 v[150:153], v[46:49], v[158:161], v[150:153]
	v_mfma_f32_16x16x32_bf16 v[146:149], v[70:73], v[158:161], v[146:149]
	v_mfma_f32_16x16x32_bf16 v[126:129], v[46:49], v[182:185], v[126:129]
	v_mfma_f32_16x16x32_bf16 v[122:125], v[70:73], v[182:185], v[122:125]
	v_mfma_f32_16x16x32_bf16 v[102:105], v[46:49], v[190:193], v[102:105]
	v_mfma_f32_16x16x32_bf16 v[98:101], v[70:73], v[190:193], v[98:101]
	s_setprio 0
	s_setprio 1
	v_mfma_f32_16x16x32_bf16 v[166:169], v[86:89], v[130:133], v[166:169]
	v_mfma_f32_16x16x32_bf16 v[130:133], v[106:109], v[130:133], v[162:165]
	v_mfma_f32_16x16x32_bf16 v[138:141], v[106:109], v[154:157], v[138:141]
	v_mfma_f32_16x16x32_bf16 v[118:121], v[86:89], v[178:181], v[118:121]
	v_mfma_f32_16x16x32_bf16 v[114:117], v[106:109], v[178:181], v[114:117]
	v_mfma_f32_16x16x32_bf16 v[94:97], v[86:89], v[186:189], v[94:97]
	v_mfma_f32_16x16x32_bf16 v[82:85], v[106:109], v[186:189], v[82:85]
	v_mfma_f32_16x16x32_bf16 v[166:169], v[90:93], v[134:137], v[166:169]
	v_mfma_f32_16x16x32_bf16 v[130:133], v[110:113], v[134:137], v[130:133]
	v_mfma_f32_16x16x32_bf16 v[134:137], v[86:89], v[154:157], v[142:145]
	v_mfma_f32_16x16x32_bf16 v[138:141], v[110:113], v[158:161], v[138:141]
	v_mfma_f32_16x16x32_bf16 v[118:121], v[90:93], v[182:185], v[118:121]
	v_mfma_f32_16x16x32_bf16 v[114:117], v[110:113], v[182:185], v[114:117]
	v_mfma_f32_16x16x32_bf16 v[94:97], v[90:93], v[190:193], v[94:97]
	v_mfma_f32_16x16x32_bf16 v[82:85], v[110:113], v[190:193], v[82:85]
	v_mfma_f32_16x16x32_bf16 v[134:137], v[90:93], v[158:161], v[134:137]
	s_setprio 0
	s_barrier
	s_mov_b64 s[58:59], s[40:41]
	ds_read_b128 v[142:145], v237 offset:16384
	ds_read_b128 v[154:157], v237 offset:17408
	ds_read_b128 v[158:161], v237 offset:18432
	ds_read_b128 v[162:165], v237 offset:19456
	ds_read_b128 v[178:181], v237 offset:20480
	ds_read_b128 v[182:185], v237 offset:21504
	ds_read_b128 v[186:189], v237 offset:22528
	ds_read_b128 v[190:193], v237 offset:23552
	s_add_i32 s60, s60, s45
	v_lshl_add_u64 v[194:195], s[58:59], 0, v[202:203]
	s_add_u32 s58, s58, 0x40000
	s_mov_b32 m0, s60
	s_addc_u32 s59, s59, 0
	global_load_lds_dwordx4 v[194:195], off
	s_add_i32 m0, s60, 0x2000
	v_lshl_add_u64 v[194:195], s[58:59], 0, v[202:203]
	s_add_u32 s58, s40, 0x80000
	s_addc_u32 s59, s41, 0
	global_load_lds_dwordx4 v[194:195], off
	s_add_i32 s60, s61, s45
	v_lshl_add_u64 v[194:195], s[58:59], 0, v[202:203]
	s_add_u32 s58, s58, 0x40000
	s_mov_b32 m0, s60
	s_addc_u32 s59, s59, 0
	global_load_lds_dwordx4 v[194:195], off
	s_add_i32 m0, s60, 0x2000
	v_lshl_add_u64 v[194:195], s[58:59], 0, v[202:203]
	s_mov_b64 s[58:59], s[42:43]
	global_load_lds_dwordx4 v[194:195], off
	s_waitcnt vmcnt(6)
	s_waitcnt lgkmcnt(0)
	s_barrier
	s_setprio 1
	s_waitcnt lgkmcnt(0)
	v_mfma_f32_16x16x32_bf16 v[78:81], v[42:45], v[142:145], v[78:81]
	v_mfma_f32_16x16x32_bf16 v[74:77], v[66:69], v[142:145], v[74:77]
	s_mov_b32 m0, s46
	v_mfma_f32_16x16x32_bf16 v[54:57], v[42:45], v[158:161], v[54:57]
	v_mfma_f32_16x16x32_bf16 v[50:53], v[66:69], v[158:161], v[50:53]
	global_load_lds_dwordx4 v208, s[42:43]
	v_mfma_f32_16x16x32_bf16 v[30:33], v[42:45], v[178:181], v[30:33]
	v_mfma_f32_16x16x32_bf16 v[26:29], v[66:69], v[178:181], v[26:29]
	s_add_u32 s100, s42, 0x40000
	v_mfma_f32_16x16x32_bf16 v[14:17], v[42:45], v[186:189], v[14:17]
	s_addc_u32 s101, s43, 0
	v_mfma_f32_16x16x32_bf16 v[10:13], v[66:69], v[186:189], v[10:13]
	s_mov_b32 m0, s47
	v_mfma_f32_16x16x32_bf16 v[78:81], v[46:49], v[154:157], v[78:81]
	v_mfma_f32_16x16x32_bf16 v[74:77], v[70:73], v[154:157], v[74:77]
	global_load_lds_dwordx4 v208, s[100:101]
	v_mfma_f32_16x16x32_bf16 v[54:57], v[46:49], v[162:165], v[54:57]
	v_mfma_f32_16x16x32_bf16 v[50:53], v[70:73], v[162:165], v[50:53]
	v_mfma_f32_16x16x32_bf16 v[30:33], v[46:49], v[182:185], v[30:33]
	v_mfma_f32_16x16x32_bf16 v[26:29], v[70:73], v[182:185], v[26:29]
	v_mfma_f32_16x16x32_bf16 v[14:17], v[46:49], v[190:193], v[14:17]
	v_mfma_f32_16x16x32_bf16 v[10:13], v[70:73], v[190:193], v[10:13]
	s_setprio 0
	s_setprio 1
	v_mfma_f32_16x16x32_bf16 v[38:41], v[86:89], v[158:161], v[38:41]
	v_mfma_f32_16x16x32_bf16 v[34:37], v[106:109], v[158:161], v[34:37]
	v_mfma_f32_16x16x32_bf16 v[22:25], v[86:89], v[178:181], v[22:25]
	v_mfma_f32_16x16x32_bf16 v[18:21], v[106:109], v[178:181], v[18:21]
	v_mfma_f32_16x16x32_bf16 v[6:9], v[86:89], v[186:189], v[6:9]
	v_mfma_f32_16x16x32_bf16 v[2:5], v[106:109], v[186:189], v[2:5]
	v_mfma_f32_16x16x32_bf16 v[42:45], v[86:89], v[142:145], v[62:65]
	v_mfma_f32_16x16x32_bf16 v[46:49], v[106:109], v[142:145], v[58:61]
	v_mfma_f32_16x16x32_bf16 v[38:41], v[90:93], v[162:165], v[38:41]
	v_mfma_f32_16x16x32_bf16 v[34:37], v[110:113], v[162:165], v[34:37]
	v_mfma_f32_16x16x32_bf16 v[22:25], v[90:93], v[182:185], v[22:25]
	v_mfma_f32_16x16x32_bf16 v[18:21], v[110:113], v[182:185], v[18:21]
	v_mfma_f32_16x16x32_bf16 v[6:9], v[90:93], v[190:193], v[6:9]
	v_mfma_f32_16x16x32_bf16 v[2:5], v[110:113], v[190:193], v[2:5]
	v_mfma_f32_16x16x32_bf16 v[42:45], v[90:93], v[154:157], v[42:45]
	v_mfma_f32_16x16x32_bf16 v[46:49], v[110:113], v[154:157], v[46:49]
	s_setprio 0
	s_barrier
	s_add_i32 s58, 0, 0x18000
	s_add_i32 s59, 0, 0x1c000
	v_add_u32_e32 v70, s58, v207
	v_add_u32_e32 v110, s59, v207
	ds_read_b128 v[58:61], v70
	ds_read_b128 v[62:65], v70 offset:1024
	ds_read_b128 v[66:69], v70 offset:2048
	ds_read_b128 v[70:73], v70 offset:3072
	ds_read_b128 v[86:89], v110
	ds_read_b128 v[90:93], v110 offset:1024
	ds_read_b128 v[106:109], v110 offset:2048
	ds_read_b128 v[110:113], v110 offset:3072
	s_add_u32 s42, s42, 0x80000
	s_addc_u32 s43, s43, 0
	ds_read_b128 v[142:145], v237 offset:32768
	ds_read_b128 v[154:157], v237 offset:33792
	ds_read_b128 v[158:161], v237 offset:34816
	ds_read_b128 v[178:181], v237 offset:35840
	ds_read_b128 v[182:185], v237 offset:36864
	ds_read_b128 v[186:189], v237 offset:37888
	ds_read_b128 v[190:193], v237 offset:38912
	ds_read_b128 v[194:197], v237 offset:39936
	s_mov_b32 m0, s48
	v_lshl_add_u64 v[162:163], s[42:43], 0, v[208:209]
	s_add_u32 s42, s42, 0x40000
	s_addc_u32 s43, s43, 0
	global_load_lds_dwordx4 v[162:163], off
	s_mov_b32 m0, s49
	v_lshl_add_u64 v[162:163], s[42:43], 0, v[208:209]
	global_load_lds_dwordx4 v[162:163], off
	s_waitcnt vmcnt(8)
	s_waitcnt lgkmcnt(0)
	s_barrier
	s_setprio 1
	s_waitcnt lgkmcnt(0)
	v_mfma_f32_16x16x32_bf16 v[162:165], v[58:61], v[142:145], v[174:177]
	v_mfma_f32_16x16x32_bf16 v[174:177], v[62:65], v[154:157], v[162:165]
	v_mfma_f32_16x16x32_bf16 v[162:165], v[66:69], v[142:145], v[170:173]
	v_mfma_f32_16x16x32_bf16 v[150:153], v[58:61], v[158:161], v[150:153]
	v_mfma_f32_16x16x32_bf16 v[146:149], v[66:69], v[158:161], v[146:149]
	v_mfma_f32_16x16x32_bf16 v[126:129], v[58:61], v[182:185], v[126:129]
	v_mfma_f32_16x16x32_bf16 v[122:125], v[66:69], v[182:185], v[122:125]
	v_mfma_f32_16x16x32_bf16 v[102:105], v[58:61], v[190:193], v[102:105]
	v_mfma_f32_16x16x32_bf16 v[98:101], v[66:69], v[190:193], v[98:101]
	v_mfma_f32_16x16x32_bf16 v[170:173], v[70:73], v[154:157], v[162:165]
	v_mfma_f32_16x16x32_bf16 v[150:153], v[62:65], v[178:181], v[150:153]
	v_mfma_f32_16x16x32_bf16 v[146:149], v[70:73], v[178:181], v[146:149]
	v_mfma_f32_16x16x32_bf16 v[126:129], v[62:65], v[186:189], v[126:129]
	v_mfma_f32_16x16x32_bf16 v[122:125], v[70:73], v[186:189], v[122:125]
	v_mfma_f32_16x16x32_bf16 v[102:105], v[62:65], v[194:197], v[102:105]
	v_mfma_f32_16x16x32_bf16 v[98:101], v[70:73], v[194:197], v[98:101]
	s_setprio 0
	s_setprio 1
	v_mfma_f32_16x16x32_bf16 v[162:165], v[86:89], v[142:145], v[166:169]
	v_mfma_f32_16x16x32_bf16 v[130:133], v[106:109], v[142:145], v[130:133]
	v_mfma_f32_16x16x32_bf16 v[166:169], v[90:93], v[154:157], v[162:165]
	v_mfma_f32_16x16x32_bf16 v[162:165], v[110:113], v[154:157], v[130:133]
	v_mfma_f32_16x16x32_bf16 v[130:133], v[86:89], v[158:161], v[134:137]
	v_mfma_f32_16x16x32_bf16 v[142:145], v[90:93], v[178:181], v[130:133]
	v_mfma_f32_16x16x32_bf16 v[130:133], v[106:109], v[158:161], v[138:141]
	v_mfma_f32_16x16x32_bf16 v[118:121], v[86:89], v[182:185], v[118:121]
	v_mfma_f32_16x16x32_bf16 v[114:117], v[106:109], v[182:185], v[114:117]
	v_mfma_f32_16x16x32_bf16 v[94:97], v[86:89], v[190:193], v[94:97]
	v_mfma_f32_16x16x32_bf16 v[82:85], v[106:109], v[190:193], v[82:85]
	v_mfma_f32_16x16x32_bf16 v[138:141], v[110:113], v[178:181], v[130:133]
	v_mfma_f32_16x16x32_bf16 v[118:121], v[90:93], v[186:189], v[118:121]
	v_mfma_f32_16x16x32_bf16 v[114:117], v[110:113], v[186:189], v[114:117]
	v_mfma_f32_16x16x32_bf16 v[94:97], v[90:93], v[194:197], v[94:97]
	v_mfma_f32_16x16x32_bf16 v[82:85], v[110:113], v[194:197], v[82:85]
	s_setprio 0
	s_barrier
	s_add_u32 s42, s40, 0x80
	s_addc_u32 s43, s41, 0
	ds_read_b128 v[130:133], v237 offset:49152
	ds_read_b128 v[134:137], v237 offset:50176
	ds_read_b128 v[154:157], v237 offset:51200
	ds_read_b128 v[158:161], v237 offset:52224
	ds_read_b128 v[178:181], v237 offset:53248
	ds_read_b128 v[182:185], v237 offset:54272
	ds_read_b128 v[186:189], v237 offset:55296
	ds_read_b128 v[190:193], v237 offset:56320
	s_add_i32 s58, s58, s45
	v_lshl_add_u64 v[194:195], s[42:43], 0, v[202:203]
	s_mov_b32 m0, s58
	s_add_u32 s42, s42, 0x40000
	global_load_lds_dwordx4 v[194:195], off
	s_addc_u32 s43, s43, 0
	s_add_i32 m0, s58, 0x2000
	s_add_u32 s40, s40, 0x80080
	s_addc_u32 s41, s41, 0
	v_lshl_add_u64 v[194:195], s[42:43], 0, v[202:203]
	global_load_lds_dwordx4 v[194:195], off
	s_add_i32 s42, s59, s45
	v_lshl_add_u64 v[194:195], s[40:41], 0, v[202:203]
	s_add_u32 s40, s40, 0x40000
	s_mov_b32 m0, s42
	s_addc_u32 s41, s41, 0
	global_load_lds_dwordx4 v[194:195], off
	s_add_i32 m0, s42, 0x2000
	v_lshl_add_u64 v[194:195], s[40:41], 0, v[202:203]
	global_load_lds_dwordx4 v[194:195], off
	s_waitcnt vmcnt(6)
	s_waitcnt lgkmcnt(0)
	s_barrier
	s_setprio 1
	s_waitcnt lgkmcnt(0)
	v_mfma_f32_16x16x32_bf16 v[78:81], v[58:61], v[130:133], v[78:81]
	v_mfma_f32_16x16x32_bf16 v[74:77], v[66:69], v[130:133], v[74:77]
	s_mov_b32 m0, s50
	v_mfma_f32_16x16x32_bf16 v[54:57], v[58:61], v[154:157], v[54:57]
	v_mfma_f32_16x16x32_bf16 v[50:53], v[66:69], v[154:157], v[50:53]
	global_load_lds_dwordx4 v208, s[38:39]
	v_mfma_f32_16x16x32_bf16 v[30:33], v[58:61], v[178:181], v[30:33]
	v_mfma_f32_16x16x32_bf16 v[26:29], v[66:69], v[178:181], v[26:29]
	s_add_u32 s38, s38, 0x40000
	v_mfma_f32_16x16x32_bf16 v[14:17], v[58:61], v[186:189], v[14:17]
	s_addc_u32 s39, s39, 0
	v_mfma_f32_16x16x32_bf16 v[10:13], v[66:69], v[186:189], v[10:13]
	s_mov_b32 m0, s51
	v_mfma_f32_16x16x32_bf16 v[78:81], v[62:65], v[134:137], v[78:81]
	v_mfma_f32_16x16x32_bf16 v[74:77], v[70:73], v[134:137], v[74:77]
	global_load_lds_dwordx4 v208, s[38:39]
	v_mfma_f32_16x16x32_bf16 v[54:57], v[62:65], v[158:161], v[54:57]
	v_mfma_f32_16x16x32_bf16 v[50:53], v[70:73], v[158:161], v[50:53]
	v_mfma_f32_16x16x32_bf16 v[30:33], v[62:65], v[182:185], v[30:33]
	v_mfma_f32_16x16x32_bf16 v[26:29], v[70:73], v[182:185], v[26:29]
	v_mfma_f32_16x16x32_bf16 v[14:17], v[62:65], v[190:193], v[14:17]
	v_mfma_f32_16x16x32_bf16 v[10:13], v[70:73], v[190:193], v[10:13]
	s_setprio 0
	s_setprio 1
	v_mfma_f32_16x16x32_bf16 v[42:45], v[86:89], v[130:133], v[42:45]
	v_mfma_f32_16x16x32_bf16 v[62:65], v[90:93], v[134:137], v[42:45]
	v_mfma_f32_16x16x32_bf16 v[42:45], v[106:109], v[130:133], v[46:49]
	v_mfma_f32_16x16x32_bf16 v[38:41], v[86:89], v[154:157], v[38:41]
	v_mfma_f32_16x16x32_bf16 v[34:37], v[106:109], v[154:157], v[34:37]
	v_mfma_f32_16x16x32_bf16 v[22:25], v[86:89], v[178:181], v[22:25]
	v_mfma_f32_16x16x32_bf16 v[18:21], v[106:109], v[178:181], v[18:21]
	v_mfma_f32_16x16x32_bf16 v[6:9], v[86:89], v[186:189], v[6:9]
	v_mfma_f32_16x16x32_bf16 v[2:5], v[106:109], v[186:189], v[2:5]
	v_mfma_f32_16x16x32_bf16 v[58:61], v[110:113], v[134:137], v[42:45]
	v_mfma_f32_16x16x32_bf16 v[38:41], v[90:93], v[158:161], v[38:41]
	v_mfma_f32_16x16x32_bf16 v[34:37], v[110:113], v[158:161], v[34:37]
	v_mfma_f32_16x16x32_bf16 v[22:25], v[90:93], v[182:185], v[22:25]
	v_mfma_f32_16x16x32_bf16 v[18:21], v[110:113], v[182:185], v[18:21]
	v_mfma_f32_16x16x32_bf16 v[6:9], v[90:93], v[190:193], v[6:9]
	v_mfma_f32_16x16x32_bf16 v[2:5], v[110:113], v[190:193], v[2:5]
	s_setprio 0
	s_barrier
	s_add_i32 s57, s57, 2
	s_add_u32 s19, s19, 0x100
	s_addc_u32 s54, s54, 0
	s_add_u32 s55, s55, 0x100
	s_addc_u32 s56, s56, 0
	s_cmp_gt_u32 s57, 29
	s_cbranch_scc0 .LBB0_293
	s_and_b64 vcc, exec, s[16:17]
	s_cbranch_vccz .LBB0_296
	s_barrier

	.amdhsa_kernel _Z6mk_fwd4Args
		.amdhsa_group_segment_fixed_size 0
		.amdhsa_private_segment_fixed_size 0
		.amdhsa_kernarg_size 472
		.amdhsa_user_sgpr_count 2
		.amdhsa_user_sgpr_dispatch_ptr 0
		.amdhsa_user_sgpr_queue_ptr 0
		.amdhsa_user_sgpr_kernarg_segment_ptr 1
		.amdhsa_user_sgpr_dispatch_id 0
		.amdhsa_user_sgpr_kernarg_preload_length 0
		.amdhsa_user_sgpr_kernarg_preload_offset 0
		.amdhsa_user_sgpr_private_segment_size 0
		.amdhsa_uses_dynamic_stack 0
		.amdhsa_enable_private_segment 0
		.amdhsa_system_sgpr_workgroup_id_x 1
		.amdhsa_system_sgpr_workgroup_id_y 0
		.amdhsa_system_sgpr_workgroup_id_z 0
		.amdhsa_system_sgpr_workgroup_info 0
		.amdhsa_system_vgpr_workitem_id 0
		.amdhsa_next_free_vgpr 250
				.amdhsa_next_free_sgpr 102
		.amdhsa_accum_offset 252
		.amdhsa_reserve_vcc 1
		.amdhsa_float_round_mode_32 0
		.amdhsa_float_round_mode_16_64 0
		.amdhsa_float_denorm_mode_32 3
		.amdhsa_float_denorm_mode_16_64 3
		.amdhsa_dx10_clamp 1
		.amdhsa_ieee_mode 1
		.amdhsa_fp16_overflow 0
		.amdhsa_tg_split 0
		.amdhsa_exception_fp_ieee_invalid_op 0
		.amdhsa_exception_fp_denorm_src 0
		.amdhsa_exception_fp_ieee_div_zero 0
		.amdhsa_exception_fp_ieee_overflow 0
		.amdhsa_exception_fp_ieee_underflow 0
		.amdhsa_exception_fp_ieee_inexact 0
		.amdhsa_exception_int_div_zero 0
	.end_amdhsa_kernel

amdhsa.kernels:
  - .agpr_count:     0
    .args:
      - .offset:         0
        .size:           216
        .value_kind:     by_value
      - .offset:         216
        .size:           4
        .value_kind:     hidden_block_count_x
      - .offset:         220
        .size:           4
        .value_kind:     hidden_block_count_y
      - .offset:         224
        .size:           4
        .value_kind:     hidden_block_count_z
      - .offset:         228
        .size:           2
        .value_kind:     hidden_group_size_x
      - .offset:         230
        .size:           2
        .value_kind:     hidden_group_size_y
      - .offset:         232
        .size:           2
        .value_kind:     hidden_group_size_z
      - .offset:         234
        .size:           2
        .value_kind:     hidden_remainder_x
      - .offset:         236
        .size:           2
        .value_kind:     hidden_remainder_y
      - .offset:         238
        .size:           2
        .value_kind:     hidden_remainder_z
      - .offset:         256
        .size:           8
        .value_kind:     hidden_global_offset_x
      - .offset:         264
        .size:           8
        .value_kind:     hidden_global_offset_y
      - .offset:         272
        .size:           8
        .value_kind:     hidden_global_offset_z
      - .offset:         280
        .size:           2
        .value_kind:     hidden_grid_dims
      - .offset:         336
        .size:           4
        .value_kind:     hidden_dynamic_lds_size
    .group_segment_fixed_size: 0
    .kernarg_segment_align: 8
    .kernarg_segment_size: 472
    .language:       OpenCL C
    .language_version:
      - 2
      - 0
    .max_flat_workgroup_size: 512
    .name:           _Z6mk_fwd4Args
    .private_segment_fixed_size: 0
    .sgpr_count:     108
    .sgpr_spill_count: 124
    .symbol:         _Z6mk_fwd4Args.kd
    .uniform_work_group_size: 1
    .uses_dynamic_stack: false
    .vgpr_count:     250
    .vgpr_spill_count: 0
    .wavefront_size: 64
